# XCD barrier: waiting workgroups poll the top-level generation word directly (no per-XCD relay on the release path)
# speedup vs baseline: 1.0053x; 1.0053x over previous
.LBB0_96:
	s_or_b64 exec, exec, s[8:9]
	v_cvt_f32_u32_e32 v4, v2
	s_waitcnt vmcnt(0)
	v_readfirstlane_b32 s1, v3
	v_sub_u32_e32 v3, 0, v2
	v_rcp_iflag_f32_e32 v4, v4
	v_add_u32_e32 v5, s1, v1
	v_mul_f32_e32 v4, 0x4f7ffffe, v4
	v_cvt_u32_f32_e32 v4, v4
	v_mul_lo_u32 v1, v3, v4
	v_mul_hi_u32 v1, v4, v1
	v_add_u32_e32 v1, v4, v1
	v_mul_hi_u32 v1, v5, v1
	v_mul_lo_u32 v3, v1, v2
	v_sub_u32_e32 v3, v5, v3
	v_add_u32_e32 v4, 1, v1
	v_cmp_ge_u32_e32 vcc, v3, v2
	s_nop 1
	v_cndmask_b32_e32 v1, v1, v4, vcc
	v_sub_u32_e32 v4, v3, v2
	v_cndmask_b32_e32 v3, v3, v4, vcc
	v_add_u32_e32 v4, 1, v1
	v_cmp_ge_u32_e32 vcc, v3, v2
	v_add_u32_e32 v3, 1, v5
	s_nop 0
	v_cndmask_b32_e32 v1, v1, v4, vcc
	v_mul_lo_u32 v4, v2, v1
	v_add_u32_e32 v2, v4, v2
	v_cmp_ne_u32_e32 vcc, v3, v2
	s_and_saveexec_b64 s[6:7], vcc
	s_xor_b64 s[6:7], exec, s[6:7]
	s_cbranch_execz .LBB0_110
	s_waitcnt lgkmcnt(0)
	v_readlane_b32 s98, v254, 38
	s_nop 3
	s_lshl_b32 s98, s98, 8
	s_sub_u32 s98, s4, s98
	s_subb_u32 s99, s5, 0
	s_add_u32 s14, s98, 0x3500
	s_addc_u32 s15, s99, 0
	v_mov_b32_e32 v0, 0
	global_load_dword v0, v0, s[14:15] sc1
	s_waitcnt vmcnt(0)
	v_cmp_eq_u32_e32 vcc, v0, v1
	s_and_saveexec_b64 s[8:9], vcc
	s_cbranch_execz .LBB0_109
	s_add_u32 s10, s78, 0x80200
	s_addc_u32 s11, s79, 0
	s_mov_b32 s1, 1
	s_mov_b64 s[16:17], 0
	v_mov_b32_e32 v0, 0
	s_branch .LBB0_100

.LBB0_217:
	s_or_b64 exec, exec, s[8:9]
	v_cvt_f32_u32_e32 v4, v2
	s_waitcnt vmcnt(0)
	v_readfirstlane_b32 s1, v3
	v_sub_u32_e32 v3, 0, v2
	v_rcp_iflag_f32_e32 v4, v4
	v_add_u32_e32 v5, s1, v1
	v_mul_f32_e32 v4, 0x4f7ffffe, v4
	v_cvt_u32_f32_e32 v4, v4
	v_mul_lo_u32 v1, v3, v4
	v_mul_hi_u32 v1, v4, v1
	v_add_u32_e32 v1, v4, v1
	v_mul_hi_u32 v1, v5, v1
	v_mul_lo_u32 v3, v1, v2
	v_sub_u32_e32 v3, v5, v3
	v_add_u32_e32 v4, 1, v1
	v_cmp_ge_u32_e32 vcc, v3, v2
	s_nop 1
	v_cndmask_b32_e32 v1, v1, v4, vcc
	v_sub_u32_e32 v4, v3, v2
	v_cndmask_b32_e32 v3, v3, v4, vcc
	v_add_u32_e32 v4, 1, v1
	v_cmp_ge_u32_e32 vcc, v3, v2
	v_add_u32_e32 v3, 1, v5
	s_nop 0
	v_cndmask_b32_e32 v1, v1, v4, vcc
	v_mul_lo_u32 v4, v2, v1
	v_add_u32_e32 v2, v4, v2
	v_cmp_ne_u32_e32 vcc, v3, v2
	s_and_saveexec_b64 s[6:7], vcc
	s_xor_b64 s[6:7], exec, s[6:7]
	s_cbranch_execz .LBB0_231
	s_waitcnt lgkmcnt(0)
	v_readlane_b32 s98, v254, 38
	s_nop 3
	s_lshl_b32 s98, s98, 8
	s_sub_u32 s98, s4, s98
	s_subb_u32 s99, s5, 0
	s_add_u32 s16, s98, 0x3500
	s_addc_u32 s17, s99, 0
	v_mov_b32_e32 v0, 0
	global_load_dword v0, v0, s[16:17] sc1
	s_waitcnt vmcnt(0)
	v_cmp_eq_u32_e32 vcc, v0, v1
	s_and_saveexec_b64 s[8:9], vcc
	s_cbranch_execz .LBB0_230
	s_add_u32 s10, s78, 0x80200
	s_addc_u32 s11, s79, 0
	s_mov_b32 s1, 1
	s_mov_b64 s[18:19], 0
	v_mov_b32_e32 v0, 0
	s_branch .LBB0_221

.LBB0_759:
	s_or_b64 exec, exec, s[6:7]
	v_cvt_f32_u32_e32 v4, v2
	s_waitcnt vmcnt(0)
	v_readfirstlane_b32 s4, v3
	v_sub_u32_e32 v3, 0, v2
	v_rcp_iflag_f32_e32 v4, v4
	v_add_u32_e32 v5, s4, v1
	v_mul_f32_e32 v4, 0x4f7ffffe, v4
	v_cvt_u32_f32_e32 v4, v4
	v_mul_lo_u32 v1, v3, v4
	v_mul_hi_u32 v1, v4, v1
	v_add_u32_e32 v1, v4, v1
	v_mul_hi_u32 v1, v5, v1
	v_mul_lo_u32 v3, v1, v2
	v_sub_u32_e32 v3, v5, v3
	v_add_u32_e32 v4, 1, v1
	v_cmp_ge_u32_e32 vcc, v3, v2
	s_nop 1
	v_cndmask_b32_e32 v1, v1, v4, vcc
	v_sub_u32_e32 v4, v3, v2
	v_cndmask_b32_e32 v3, v3, v4, vcc
	v_add_u32_e32 v4, 1, v1
	v_cmp_ge_u32_e32 vcc, v3, v2
	v_add_u32_e32 v3, 1, v5
	s_nop 0
	v_cndmask_b32_e32 v1, v1, v4, vcc
	v_mul_lo_u32 v4, v2, v1
	v_add_u32_e32 v2, v4, v2
	v_cmp_ne_u32_e32 vcc, v3, v2
	s_and_saveexec_b64 s[4:5], vcc
	s_xor_b64 s[4:5], exec, s[4:5]
	s_cbranch_execz .LBB0_773
	s_waitcnt lgkmcnt(0)
	v_readlane_b32 s98, v254, 38
	s_nop 3
	s_lshl_b32 s98, s98, 8
	s_sub_u32 s98, s2, s98
	s_subb_u32 s99, s3, 0
	s_add_u32 s10, s98, 0x3500
	s_addc_u32 s11, s99, 0
	v_mov_b32_e32 v0, 0
	global_load_dword v0, v0, s[10:11] sc1
	s_waitcnt vmcnt(0)
	v_cmp_eq_u32_e32 vcc, v0, v1
	s_and_saveexec_b64 s[6:7], vcc
	s_cbranch_execz .LBB0_772
	s_add_u32 s8, s78, 0x80200
	s_addc_u32 s9, s79, 0
	s_mov_b32 s22, 1
	s_mov_b64 s[12:13], 0
	v_mov_b32_e32 v0, 0
	s_branch .LBB0_763

.LBB0_1020:
	s_or_b64 exec, exec, s[8:9]
	v_cvt_f32_u32_e32 v4, v2
	s_waitcnt vmcnt(0)
	v_readfirstlane_b32 s6, v3
	v_sub_u32_e32 v3, 0, v2
	v_rcp_iflag_f32_e32 v4, v4
	v_add_u32_e32 v5, s6, v1
	v_mul_f32_e32 v4, 0x4f7ffffe, v4
	v_cvt_u32_f32_e32 v4, v4
	v_mul_lo_u32 v1, v3, v4
	v_mul_hi_u32 v1, v4, v1
	v_add_u32_e32 v1, v4, v1
	v_mul_hi_u32 v1, v5, v1
	v_mul_lo_u32 v3, v1, v2
	v_sub_u32_e32 v3, v5, v3
	v_add_u32_e32 v4, 1, v1
	v_cmp_ge_u32_e32 vcc, v3, v2
	s_nop 1
	v_cndmask_b32_e32 v1, v1, v4, vcc
	v_sub_u32_e32 v4, v3, v2
	v_cndmask_b32_e32 v3, v3, v4, vcc
	v_add_u32_e32 v4, 1, v1
	v_cmp_ge_u32_e32 vcc, v3, v2
	v_add_u32_e32 v3, 1, v5
	s_nop 0
	v_cndmask_b32_e32 v1, v1, v4, vcc
	v_mul_lo_u32 v4, v2, v1
	v_add_u32_e32 v2, v4, v2
	v_cmp_ne_u32_e32 vcc, v3, v2
	s_and_saveexec_b64 s[6:7], vcc
	s_xor_b64 s[6:7], exec, s[6:7]
	s_cbranch_execz .LBB0_1034
	s_waitcnt lgkmcnt(0)
	v_readlane_b32 s98, v254, 38
	s_nop 3
	s_lshl_b32 s98, s98, 8
	s_sub_u32 s98, s4, s98
	s_subb_u32 s99, s5, 0
	s_add_u32 s12, s98, 0x3500
	s_addc_u32 s13, s99, 0
	v_mov_b32_e32 v0, 0
	global_load_dword v0, v0, s[12:13] sc1
	s_waitcnt vmcnt(0)
	v_cmp_eq_u32_e32 vcc, v0, v1
	s_and_saveexec_b64 s[8:9], vcc
	s_cbranch_execz .LBB0_1033
	s_add_u32 s10, s78, 0x80200
	s_addc_u32 s11, s79, 0
	s_mov_b32 s24, 1
	s_mov_b64 s[14:15], 0
	v_mov_b32_e32 v0, 0
	s_branch .LBB0_1024

.LBB0_1114:
	s_or_b64 exec, exec, s[6:7]
	v_cvt_f32_u32_e32 v4, v2
	s_waitcnt vmcnt(0)
	v_readfirstlane_b32 s4, v3
	v_sub_u32_e32 v3, 0, v2
	v_rcp_iflag_f32_e32 v4, v4
	v_add_u32_e32 v5, s4, v1
	v_mul_f32_e32 v4, 0x4f7ffffe, v4
	v_cvt_u32_f32_e32 v4, v4
	v_mul_lo_u32 v1, v3, v4
	v_mul_hi_u32 v1, v4, v1
	v_add_u32_e32 v1, v4, v1
	v_mul_hi_u32 v1, v5, v1
	v_mul_lo_u32 v3, v1, v2
	v_sub_u32_e32 v3, v5, v3
	v_add_u32_e32 v4, 1, v1
	v_cmp_ge_u32_e32 vcc, v3, v2
	s_nop 1
	v_cndmask_b32_e32 v1, v1, v4, vcc
	v_sub_u32_e32 v4, v3, v2
	v_cndmask_b32_e32 v3, v3, v4, vcc
	v_add_u32_e32 v4, 1, v1
	v_cmp_ge_u32_e32 vcc, v3, v2
	v_add_u32_e32 v3, 1, v5
	s_nop 0
	v_cndmask_b32_e32 v1, v1, v4, vcc
	v_mul_lo_u32 v4, v2, v1
	v_add_u32_e32 v2, v4, v2
	v_cmp_ne_u32_e32 vcc, v3, v2
	s_and_saveexec_b64 s[4:5], vcc
	s_xor_b64 s[4:5], exec, s[4:5]
	s_cbranch_execz .LBB0_1128
	s_waitcnt lgkmcnt(0)
	v_readlane_b32 s98, v254, 38
	s_nop 3
	s_lshl_b32 s98, s98, 8
	s_sub_u32 s98, s2, s98
	s_subb_u32 s99, s3, 0
	s_add_u32 s10, s98, 0x3500
	s_addc_u32 s11, s99, 0
	v_mov_b32_e32 v0, 0
	global_load_dword v0, v0, s[10:11] sc1
	s_waitcnt vmcnt(0)
	v_cmp_eq_u32_e32 vcc, v0, v1
	s_and_saveexec_b64 s[6:7], vcc
	s_cbranch_execz .LBB0_1127
	s_add_u32 s8, s78, 0x80200
	s_addc_u32 s9, s79, 0
	s_mov_b32 s24, 1
	s_mov_b64 s[14:15], 0
	v_mov_b32_e32 v0, 0
	s_branch .LBB0_1118

.LBB0_1244:
	s_or_b64 exec, exec, s[6:7]
	v_cvt_f32_u32_e32 v4, v2
	s_waitcnt vmcnt(0)
	v_readfirstlane_b32 s4, v3
	v_sub_u32_e32 v3, 0, v2
	v_rcp_iflag_f32_e32 v4, v4
	v_add_u32_e32 v5, s4, v1
	v_mul_f32_e32 v4, 0x4f7ffffe, v4
	v_cvt_u32_f32_e32 v4, v4
	v_mul_lo_u32 v1, v3, v4
	v_mul_hi_u32 v1, v4, v1
	v_add_u32_e32 v1, v4, v1
	v_mul_hi_u32 v1, v5, v1
	v_mul_lo_u32 v3, v1, v2
	v_sub_u32_e32 v3, v5, v3
	v_add_u32_e32 v4, 1, v1
	v_cmp_ge_u32_e32 vcc, v3, v2
	s_nop 1
	v_cndmask_b32_e32 v1, v1, v4, vcc
	v_sub_u32_e32 v4, v3, v2
	v_cndmask_b32_e32 v3, v3, v4, vcc
	v_add_u32_e32 v4, 1, v1
	v_cmp_ge_u32_e32 vcc, v3, v2
	v_add_u32_e32 v3, 1, v5
	s_nop 0
	v_cndmask_b32_e32 v1, v1, v4, vcc
	v_mul_lo_u32 v4, v2, v1
	v_add_u32_e32 v2, v4, v2
	v_cmp_ne_u32_e32 vcc, v3, v2
	s_and_saveexec_b64 s[4:5], vcc
	s_xor_b64 s[4:5], exec, s[4:5]
	s_cbranch_execz .LBB0_1258
	s_waitcnt lgkmcnt(0)
	v_readlane_b32 s98, v254, 38
	s_nop 3
	s_lshl_b32 s98, s98, 8
	s_sub_u32 s98, s2, s98
	s_subb_u32 s99, s3, 0
	s_add_u32 s10, s98, 0x3500
	s_addc_u32 s11, s99, 0
	v_mov_b32_e32 v0, 0
	global_load_dword v0, v0, s[10:11] sc1
	s_waitcnt vmcnt(0)
	v_cmp_eq_u32_e32 vcc, v0, v1
	s_and_saveexec_b64 s[6:7], vcc
	s_cbranch_execz .LBB0_1257
	s_add_u32 s8, s78, 0x80200
	s_addc_u32 s9, s79, 0
	s_mov_b32 s26, 1
	s_mov_b64 s[16:17], 0
	v_mov_b32_e32 v0, 0
	s_branch .LBB0_1248
